# P4 compress stage 2 triple-row pass with four load buffers (prefetch distance three chunks)
# baseline (speedup 1.0000x reference)
.LBB0_648:
	s_mul_hi_i32 s2, s26, 0x2ad5802b
	s_lshr_b32 s3, s2, 31
	s_ashr_i32 s2, s2, 10
	s_add_i32 s28, s2, s3
	v_lshl_or_b32 v16, s28, 6, v229
	v_ashrrev_i32_e32 v17, 31, v16
	v_lshl_add_u64 v[16:17], v[16:17], 2, v[2:3]
	global_load_dword v6, v[16:17], off
	s_mul_i32 s2, s28, 0x17e8
	s_sub_i32 s14, s26, s2
	s_ashr_i32 s29, s28, 31
	s_mul_i32 s2, s28, 0x1800
	s_ashr_i32 s15, s14, 31
	s_mul_hi_i32 s3, s28, 0x1800
	s_add_u32 s2, s2, s14
	s_addc_u32 s3, s3, s15
	s_lshl_b64 s[2:3], s[2:3], 9
	s_add_u32 s2, s16, s2
	s_addc_u32 s3, s21, s3
	s_lshl_b64 s[28:29], s[28:29], 16
	v_mov_b32_e32 v9, 0
	v_lshl_add_u64 v[16:17], v[0:1], 0, s[28:29]
	s_mov_b32 s15, -2
	v_mov_b32_e32 v18, 0
	v_mov_b32_e32 v19, v9
	s_lshl_b32 s80, s54, 1
	s_add_i32 s80, s80, s26
	s_cmp_lt_i32 s80, 0x2fd0
	s_cbranch_scc0 .Lc3_single
	s_cmp_ge_i32 s26, 0x17e8
	s_cselect_b32 s81, 1, 0
	s_cmp_ge_i32 s80, 0x17e8
	s_cselect_b32 s80, 1, 0
	s_cmp_lg_u32 s80, s81
	s_cbranch_scc1 .Lc3_single
	s_sub_i32 s79, s26, s14
	s_lshl_b32 s80, s54, 9
	s_mov_b64 s[60:61], s[2:3]
	s_add_u32 s64, s2, s80
	s_addc_u32 s65, s3, 0
	s_add_u32 s72, s64, s80
	s_addc_u32 s73, s65, 0
	s_mov_b64 s[82:83], 0x1000
	v_mov_b32_e32 v167, 0
	v_mov_b32_e32 v178, v16
	v_mov_b32_e32 v179, v17
	v_lshl_add_u64 v[232:233], v[178:179], 0, s[82:83]
	v_lshl_add_u64 v[234:235], v[232:233], 0, s[82:83]
	v_lshl_add_u64 v[236:237], v[234:235], 0, s[82:83]
	s_mov_b64 s[82:83], 0x2000
	global_load_dwordx4 v[72:75], v167, s[60:61]
	global_load_dwordx4 v[76:79], v167, s[64:65]
	global_load_dwordx4 v[80:83], v167, s[72:73]
	global_load_dword v96, v[178:179], off
	global_load_dword v97, v[178:179], off offset:256
	global_load_dword v98, v[178:179], off offset:512
	global_load_dword v99, v[178:179], off offset:768
	global_load_dword v100, v[178:179], off offset:1024
	global_load_dword v101, v[178:179], off offset:1280
	global_load_dword v102, v[178:179], off offset:1536
	global_load_dword v103, v[178:179], off offset:1792
	global_load_dwordx4 v[84:87], v167, s[60:61] offset:16
	global_load_dwordx4 v[88:91], v167, s[64:65] offset:16
	global_load_dwordx4 v[92:95], v167, s[72:73] offset:16
	global_load_dword v104, v[178:179], off offset:2048
	global_load_dword v105, v[178:179], off offset:2304
	global_load_dword v106, v[178:179], off offset:2560
	global_load_dword v107, v[178:179], off offset:2816
	global_load_dword v108, v[178:179], off offset:3072
	global_load_dword v109, v[178:179], off offset:3328
	global_load_dword v110, v[178:179], off offset:3584
	global_load_dword v111, v[178:179], off offset:3840
	global_load_dwordx4 v[186:189], v167, s[60:61] offset:32
	global_load_dwordx4 v[190:193], v167, s[64:65] offset:32
	global_load_dwordx4 v[194:197], v167, s[72:73] offset:32
	global_load_dword v198, v[232:233], off
	global_load_dword v199, v[232:233], off offset:256
	global_load_dword v200, v[232:233], off offset:512
	global_load_dword v201, v[232:233], off offset:768
	global_load_dword v202, v[232:233], off offset:1024
	global_load_dword v203, v[232:233], off offset:1280
	global_load_dword v204, v[232:233], off offset:1536
	global_load_dword v205, v[232:233], off offset:1792
	v_mov_b32_e32 v61, 0
	v_mov_b32_e32 v62, 0
	v_mov_b32_e32 v63, 0
	v_mov_b32_e32 v65, 0
	v_mov_b32_e32 v66, 0
	v_mov_b32_e32 v67, 0
	v_mov_b32_e32 v69, 0
	v_mov_b32_e32 v70, 0
	v_mov_b32_e32 v71, 0
	s_mov_b32 s77, 0
	s_waitcnt vmcnt(33)
	v_mov_b32_e32 v60, v6
	v_mov_b32_e32 v64, v6
	v_mov_b32_e32 v68, v6
.Lc3_loop:
	global_load_dwordx4 v[206:209], v167, s[60:61] offset:48
	global_load_dwordx4 v[210:213], v167, s[64:65] offset:48
	global_load_dwordx4 v[214:217], v167, s[72:73] offset:48
	global_load_dword v218, v[232:233], off offset:2048
	global_load_dword v219, v[232:233], off offset:2304
	global_load_dword v220, v[232:233], off offset:2560
	global_load_dword v221, v[232:233], off offset:2816
	global_load_dword v222, v[232:233], off offset:3072
	global_load_dword v223, v[232:233], off offset:3328
	global_load_dword v224, v[232:233], off offset:3584
	global_load_dword v225, v[232:233], off offset:3840
	s_waitcnt vmcnt(33)
	v_lshlrev_b32_e32 v165, 16, v72
	v_and_b32_e32 v166, 0xffff0000, v72
	v_fmac_f32_e32 v60, v165, v96
	v_fmac_f32_e32 v61, v166, v97
	v_lshlrev_b32_e32 v59, 16, v76
	v_and_b32_e32 v177, 0xffff0000, v76
	v_fmac_f32_e32 v64, v59, v96
	v_fmac_f32_e32 v65, v177, v97
	v_lshlrev_b32_e32 v165, 16, v80
	v_and_b32_e32 v166, 0xffff0000, v80
	v_fmac_f32_e32 v68, v165, v96
	v_fmac_f32_e32 v69, v166, v97
	v_lshlrev_b32_e32 v165, 16, v73
	v_and_b32_e32 v166, 0xffff0000, v73
	v_fmac_f32_e32 v62, v165, v98
	v_fmac_f32_e32 v63, v166, v99
	v_lshlrev_b32_e32 v59, 16, v77
	v_and_b32_e32 v177, 0xffff0000, v77
	v_fmac_f32_e32 v66, v59, v98
	v_fmac_f32_e32 v67, v177, v99
	v_lshlrev_b32_e32 v165, 16, v81
	v_and_b32_e32 v166, 0xffff0000, v81
	v_fmac_f32_e32 v70, v165, v98
	v_fmac_f32_e32 v71, v166, v99
	v_lshlrev_b32_e32 v165, 16, v74
	v_and_b32_e32 v166, 0xffff0000, v74
	v_fmac_f32_e32 v60, v165, v100
	v_fmac_f32_e32 v61, v166, v101
	v_lshlrev_b32_e32 v59, 16, v78
	v_and_b32_e32 v177, 0xffff0000, v78
	v_fmac_f32_e32 v64, v59, v100
	v_fmac_f32_e32 v65, v177, v101
	v_lshlrev_b32_e32 v165, 16, v82
	v_and_b32_e32 v166, 0xffff0000, v82
	v_fmac_f32_e32 v68, v165, v100
	v_fmac_f32_e32 v69, v166, v101
	v_lshlrev_b32_e32 v165, 16, v75
	v_and_b32_e32 v166, 0xffff0000, v75
	v_fmac_f32_e32 v62, v165, v102
	v_fmac_f32_e32 v63, v166, v103
	v_lshlrev_b32_e32 v59, 16, v79
	v_and_b32_e32 v177, 0xffff0000, v79
	v_fmac_f32_e32 v66, v59, v102
	v_fmac_f32_e32 v67, v177, v103
	v_lshlrev_b32_e32 v165, 16, v83
	v_and_b32_e32 v166, 0xffff0000, v83
	v_fmac_f32_e32 v70, v165, v102
	v_fmac_f32_e32 v71, v166, v103
	global_load_dwordx4 v[72:75], v167, s[60:61] offset:64
	global_load_dwordx4 v[76:79], v167, s[64:65] offset:64
	global_load_dwordx4 v[80:83], v167, s[72:73] offset:64
	global_load_dword v96, v[234:235], off
	global_load_dword v97, v[234:235], off offset:256
	global_load_dword v98, v[234:235], off offset:512
	global_load_dword v99, v[234:235], off offset:768
	global_load_dword v100, v[234:235], off offset:1024
	global_load_dword v101, v[234:235], off offset:1280
	global_load_dword v102, v[234:235], off offset:1536
	global_load_dword v103, v[234:235], off offset:1792
	s_waitcnt vmcnt(33)
	v_lshlrev_b32_e32 v165, 16, v84
	v_and_b32_e32 v166, 0xffff0000, v84
	v_fmac_f32_e32 v60, v165, v104
	v_fmac_f32_e32 v61, v166, v105
	v_lshlrev_b32_e32 v59, 16, v88
	v_and_b32_e32 v177, 0xffff0000, v88
	v_fmac_f32_e32 v64, v59, v104
	v_fmac_f32_e32 v65, v177, v105
	v_lshlrev_b32_e32 v165, 16, v92
	v_and_b32_e32 v166, 0xffff0000, v92
	v_fmac_f32_e32 v68, v165, v104
	v_fmac_f32_e32 v69, v166, v105
	v_lshlrev_b32_e32 v165, 16, v85
	v_and_b32_e32 v166, 0xffff0000, v85
	v_fmac_f32_e32 v62, v165, v106
	v_fmac_f32_e32 v63, v166, v107
	v_lshlrev_b32_e32 v59, 16, v89
	v_and_b32_e32 v177, 0xffff0000, v89
	v_fmac_f32_e32 v66, v59, v106
	v_fmac_f32_e32 v67, v177, v107
	v_lshlrev_b32_e32 v165, 16, v93
	v_and_b32_e32 v166, 0xffff0000, v93
	v_fmac_f32_e32 v70, v165, v106
	v_fmac_f32_e32 v71, v166, v107
	v_lshlrev_b32_e32 v165, 16, v86
	v_and_b32_e32 v166, 0xffff0000, v86
	v_fmac_f32_e32 v60, v165, v108
	v_fmac_f32_e32 v61, v166, v109
	v_lshlrev_b32_e32 v59, 16, v90
	v_and_b32_e32 v177, 0xffff0000, v90
	v_fmac_f32_e32 v64, v59, v108
	v_fmac_f32_e32 v65, v177, v109
	v_lshlrev_b32_e32 v165, 16, v94
	v_and_b32_e32 v166, 0xffff0000, v94
	v_fmac_f32_e32 v68, v165, v108
	v_fmac_f32_e32 v69, v166, v109
	v_lshlrev_b32_e32 v165, 16, v87
	v_and_b32_e32 v166, 0xffff0000, v87
	v_fmac_f32_e32 v62, v165, v110
	v_fmac_f32_e32 v63, v166, v111
	v_lshlrev_b32_e32 v59, 16, v91
	v_and_b32_e32 v177, 0xffff0000, v91
	v_fmac_f32_e32 v66, v59, v110
	v_fmac_f32_e32 v67, v177, v111
	v_lshlrev_b32_e32 v165, 16, v95
	v_and_b32_e32 v166, 0xffff0000, v95
	v_fmac_f32_e32 v70, v165, v110
	v_fmac_f32_e32 v71, v166, v111
	global_load_dwordx4 v[84:87], v167, s[60:61] offset:80
	global_load_dwordx4 v[88:91], v167, s[64:65] offset:80
	global_load_dwordx4 v[92:95], v167, s[72:73] offset:80
	global_load_dword v104, v[234:235], off offset:2048
	global_load_dword v105, v[234:235], off offset:2304
	global_load_dword v106, v[234:235], off offset:2560
	global_load_dword v107, v[234:235], off offset:2816
	global_load_dword v108, v[234:235], off offset:3072
	global_load_dword v109, v[234:235], off offset:3328
	global_load_dword v110, v[234:235], off offset:3584
	global_load_dword v111, v[234:235], off offset:3840
	s_waitcnt vmcnt(33)
	v_lshlrev_b32_e32 v165, 16, v186
	v_and_b32_e32 v166, 0xffff0000, v186
	v_fmac_f32_e32 v60, v165, v198
	v_fmac_f32_e32 v61, v166, v199
	v_lshlrev_b32_e32 v59, 16, v190
	v_and_b32_e32 v177, 0xffff0000, v190
	v_fmac_f32_e32 v64, v59, v198
	v_fmac_f32_e32 v65, v177, v199
	v_lshlrev_b32_e32 v165, 16, v194
	v_and_b32_e32 v166, 0xffff0000, v194
	v_fmac_f32_e32 v68, v165, v198
	v_fmac_f32_e32 v69, v166, v199
	v_lshlrev_b32_e32 v165, 16, v187
	v_and_b32_e32 v166, 0xffff0000, v187
	v_fmac_f32_e32 v62, v165, v200
	v_fmac_f32_e32 v63, v166, v201
	v_lshlrev_b32_e32 v59, 16, v191
	v_and_b32_e32 v177, 0xffff0000, v191
	v_fmac_f32_e32 v66, v59, v200
	v_fmac_f32_e32 v67, v177, v201
	v_lshlrev_b32_e32 v165, 16, v195
	v_and_b32_e32 v166, 0xffff0000, v195
	v_fmac_f32_e32 v70, v165, v200
	v_fmac_f32_e32 v71, v166, v201
	v_lshlrev_b32_e32 v165, 16, v188
	v_and_b32_e32 v166, 0xffff0000, v188
	v_fmac_f32_e32 v60, v165, v202
	v_fmac_f32_e32 v61, v166, v203
	v_lshlrev_b32_e32 v59, 16, v192
	v_and_b32_e32 v177, 0xffff0000, v192
	v_fmac_f32_e32 v64, v59, v202
	v_fmac_f32_e32 v65, v177, v203
	v_lshlrev_b32_e32 v165, 16, v196
	v_and_b32_e32 v166, 0xffff0000, v196
	v_fmac_f32_e32 v68, v165, v202
	v_fmac_f32_e32 v69, v166, v203
	v_lshlrev_b32_e32 v165, 16, v189
	v_and_b32_e32 v166, 0xffff0000, v189
	v_fmac_f32_e32 v62, v165, v204
	v_fmac_f32_e32 v63, v166, v205
	v_lshlrev_b32_e32 v59, 16, v193
	v_and_b32_e32 v177, 0xffff0000, v193
	v_fmac_f32_e32 v66, v59, v204
	v_fmac_f32_e32 v67, v177, v205
	v_lshlrev_b32_e32 v165, 16, v197
	v_and_b32_e32 v166, 0xffff0000, v197
	v_fmac_f32_e32 v70, v165, v204
	v_fmac_f32_e32 v71, v166, v205
	global_load_dwordx4 v[186:189], v167, s[60:61] offset:96
	global_load_dwordx4 v[190:193], v167, s[64:65] offset:96
	global_load_dwordx4 v[194:197], v167, s[72:73] offset:96
	global_load_dword v198, v[236:237], off
	global_load_dword v199, v[236:237], off offset:256
	global_load_dword v200, v[236:237], off offset:512
	global_load_dword v201, v[236:237], off offset:768
	global_load_dword v202, v[236:237], off offset:1024
	global_load_dword v203, v[236:237], off offset:1280
	global_load_dword v204, v[236:237], off offset:1536
	global_load_dword v205, v[236:237], off offset:1792
	s_waitcnt vmcnt(33)
	v_lshlrev_b32_e32 v165, 16, v206
	v_and_b32_e32 v166, 0xffff0000, v206
	v_fmac_f32_e32 v60, v165, v218
	v_fmac_f32_e32 v61, v166, v219
	v_lshlrev_b32_e32 v59, 16, v210
	v_and_b32_e32 v177, 0xffff0000, v210
	v_fmac_f32_e32 v64, v59, v218
	v_fmac_f32_e32 v65, v177, v219
	v_lshlrev_b32_e32 v165, 16, v214
	v_and_b32_e32 v166, 0xffff0000, v214
	v_fmac_f32_e32 v68, v165, v218
	v_fmac_f32_e32 v69, v166, v219
	v_lshlrev_b32_e32 v165, 16, v207
	v_and_b32_e32 v166, 0xffff0000, v207
	v_fmac_f32_e32 v62, v165, v220
	v_fmac_f32_e32 v63, v166, v221
	v_lshlrev_b32_e32 v59, 16, v211
	v_and_b32_e32 v177, 0xffff0000, v211
	v_fmac_f32_e32 v66, v59, v220
	v_fmac_f32_e32 v67, v177, v221
	v_lshlrev_b32_e32 v165, 16, v215
	v_and_b32_e32 v166, 0xffff0000, v215
	v_fmac_f32_e32 v70, v165, v220
	v_fmac_f32_e32 v71, v166, v221
	v_lshlrev_b32_e32 v165, 16, v208
	v_and_b32_e32 v166, 0xffff0000, v208
	v_fmac_f32_e32 v60, v165, v222
	v_fmac_f32_e32 v61, v166, v223
	v_lshlrev_b32_e32 v59, 16, v212
	v_and_b32_e32 v177, 0xffff0000, v212
	v_fmac_f32_e32 v64, v59, v222
	v_fmac_f32_e32 v65, v177, v223
	v_lshlrev_b32_e32 v165, 16, v216
	v_and_b32_e32 v166, 0xffff0000, v216
	v_fmac_f32_e32 v68, v165, v222
	v_fmac_f32_e32 v69, v166, v223
	v_lshlrev_b32_e32 v165, 16, v209
	v_and_b32_e32 v166, 0xffff0000, v209
	v_fmac_f32_e32 v62, v165, v224
	v_fmac_f32_e32 v63, v166, v225
	v_lshlrev_b32_e32 v59, 16, v213
	v_and_b32_e32 v177, 0xffff0000, v213
	v_fmac_f32_e32 v66, v59, v224
	v_fmac_f32_e32 v67, v177, v225
	v_lshlrev_b32_e32 v165, 16, v217
	v_and_b32_e32 v166, 0xffff0000, v217
	v_fmac_f32_e32 v70, v165, v224
	v_fmac_f32_e32 v71, v166, v225
	s_add_u32 s60, s60, 64
	s_addc_u32 s61, s61, 0
	s_add_u32 s64, s64, 64
	s_addc_u32 s65, s65, 0
	s_add_u32 s72, s72, 64
	s_addc_u32 s73, s73, 0
	v_lshl_add_u64 v[178:179], v[178:179], 0, s[82:83]
	v_lshl_add_u64 v[232:233], v[232:233], 0, s[82:83]
	v_lshl_add_u64 v[234:235], v[234:235], 0, s[82:83]
	v_lshl_add_u64 v[236:237], v[236:237], 0, s[82:83]
	s_add_u32 s77, s77, 1
	s_cmp_lt_u32 s77, 7
	s_cbranch_scc1 .Lc3_loop
	global_load_dwordx4 v[206:209], v167, s[60:61] offset:48
	global_load_dwordx4 v[210:213], v167, s[64:65] offset:48
	global_load_dwordx4 v[214:217], v167, s[72:73] offset:48
	global_load_dword v218, v[232:233], off offset:2048
	global_load_dword v219, v[232:233], off offset:2304
	global_load_dword v220, v[232:233], off offset:2560
	global_load_dword v221, v[232:233], off offset:2816
	global_load_dword v222, v[232:233], off offset:3072
	global_load_dword v223, v[232:233], off offset:3328
	global_load_dword v224, v[232:233], off offset:3584
	global_load_dword v225, v[232:233], off offset:3840
	s_waitcnt vmcnt(33)
	v_lshlrev_b32_e32 v165, 16, v72
	v_and_b32_e32 v166, 0xffff0000, v72
	v_fmac_f32_e32 v60, v165, v96
	v_fmac_f32_e32 v61, v166, v97
	v_lshlrev_b32_e32 v59, 16, v76
	v_and_b32_e32 v177, 0xffff0000, v76
	v_fmac_f32_e32 v64, v59, v96
	v_fmac_f32_e32 v65, v177, v97
	v_lshlrev_b32_e32 v165, 16, v80
	v_and_b32_e32 v166, 0xffff0000, v80
	v_fmac_f32_e32 v68, v165, v96
	v_fmac_f32_e32 v69, v166, v97
	v_lshlrev_b32_e32 v165, 16, v73
	v_and_b32_e32 v166, 0xffff0000, v73
	v_fmac_f32_e32 v62, v165, v98
	v_fmac_f32_e32 v63, v166, v99
	v_lshlrev_b32_e32 v59, 16, v77
	v_and_b32_e32 v177, 0xffff0000, v77
	v_fmac_f32_e32 v66, v59, v98
	v_fmac_f32_e32 v67, v177, v99
	v_lshlrev_b32_e32 v165, 16, v81
	v_and_b32_e32 v166, 0xffff0000, v81
	v_fmac_f32_e32 v70, v165, v98
	v_fmac_f32_e32 v71, v166, v99
	v_lshlrev_b32_e32 v165, 16, v74
	v_and_b32_e32 v166, 0xffff0000, v74
	v_fmac_f32_e32 v60, v165, v100
	v_fmac_f32_e32 v61, v166, v101
	v_lshlrev_b32_e32 v59, 16, v78
	v_and_b32_e32 v177, 0xffff0000, v78
	v_fmac_f32_e32 v64, v59, v100
	v_fmac_f32_e32 v65, v177, v101
	v_lshlrev_b32_e32 v165, 16, v82
	v_and_b32_e32 v166, 0xffff0000, v82
	v_fmac_f32_e32 v68, v165, v100
	v_fmac_f32_e32 v69, v166, v101
	v_lshlrev_b32_e32 v165, 16, v75
	v_and_b32_e32 v166, 0xffff0000, v75
	v_fmac_f32_e32 v62, v165, v102
	v_fmac_f32_e32 v63, v166, v103
	v_lshlrev_b32_e32 v59, 16, v79
	v_and_b32_e32 v177, 0xffff0000, v79
	v_fmac_f32_e32 v66, v59, v102
	v_fmac_f32_e32 v67, v177, v103
	v_lshlrev_b32_e32 v165, 16, v83
	v_and_b32_e32 v166, 0xffff0000, v83
	v_fmac_f32_e32 v70, v165, v102
	v_fmac_f32_e32 v71, v166, v103
	s_waitcnt vmcnt(22)
	v_lshlrev_b32_e32 v165, 16, v84
	v_and_b32_e32 v166, 0xffff0000, v84
	v_fmac_f32_e32 v60, v165, v104
	v_fmac_f32_e32 v61, v166, v105
	v_lshlrev_b32_e32 v59, 16, v88
	v_and_b32_e32 v177, 0xffff0000, v88
	v_fmac_f32_e32 v64, v59, v104
	v_fmac_f32_e32 v65, v177, v105
	v_lshlrev_b32_e32 v165, 16, v92
	v_and_b32_e32 v166, 0xffff0000, v92
	v_fmac_f32_e32 v68, v165, v104
	v_fmac_f32_e32 v69, v166, v105
	v_lshlrev_b32_e32 v165, 16, v85
	v_and_b32_e32 v166, 0xffff0000, v85
	v_fmac_f32_e32 v62, v165, v106
	v_fmac_f32_e32 v63, v166, v107
	v_lshlrev_b32_e32 v59, 16, v89
	v_and_b32_e32 v177, 0xffff0000, v89
	v_fmac_f32_e32 v66, v59, v106
	v_fmac_f32_e32 v67, v177, v107
	v_lshlrev_b32_e32 v165, 16, v93
	v_and_b32_e32 v166, 0xffff0000, v93
	v_fmac_f32_e32 v70, v165, v106
	v_fmac_f32_e32 v71, v166, v107
	v_lshlrev_b32_e32 v165, 16, v86
	v_and_b32_e32 v166, 0xffff0000, v86
	v_fmac_f32_e32 v60, v165, v108
	v_fmac_f32_e32 v61, v166, v109
	v_lshlrev_b32_e32 v59, 16, v90
	v_and_b32_e32 v177, 0xffff0000, v90
	v_fmac_f32_e32 v64, v59, v108
	v_fmac_f32_e32 v65, v177, v109
	v_lshlrev_b32_e32 v165, 16, v94
	v_and_b32_e32 v166, 0xffff0000, v94
	v_fmac_f32_e32 v68, v165, v108
	v_fmac_f32_e32 v69, v166, v109
	v_lshlrev_b32_e32 v165, 16, v87
	v_and_b32_e32 v166, 0xffff0000, v87
	v_fmac_f32_e32 v62, v165, v110
	v_fmac_f32_e32 v63, v166, v111
	v_lshlrev_b32_e32 v59, 16, v91
	v_and_b32_e32 v177, 0xffff0000, v91
	v_fmac_f32_e32 v66, v59, v110
	v_fmac_f32_e32 v67, v177, v111
	v_lshlrev_b32_e32 v165, 16, v95
	v_and_b32_e32 v166, 0xffff0000, v95
	v_fmac_f32_e32 v70, v165, v110
	v_fmac_f32_e32 v71, v166, v111
	s_waitcnt vmcnt(11)
	v_lshlrev_b32_e32 v165, 16, v186
	v_and_b32_e32 v166, 0xffff0000, v186
	v_fmac_f32_e32 v60, v165, v198
	v_fmac_f32_e32 v61, v166, v199
	v_lshlrev_b32_e32 v59, 16, v190
	v_and_b32_e32 v177, 0xffff0000, v190
	v_fmac_f32_e32 v64, v59, v198
	v_fmac_f32_e32 v65, v177, v199
	v_lshlrev_b32_e32 v165, 16, v194
	v_and_b32_e32 v166, 0xffff0000, v194
	v_fmac_f32_e32 v68, v165, v198
	v_fmac_f32_e32 v69, v166, v199
	v_lshlrev_b32_e32 v165, 16, v187
	v_and_b32_e32 v166, 0xffff0000, v187
	v_fmac_f32_e32 v62, v165, v200
	v_fmac_f32_e32 v63, v166, v201
	v_lshlrev_b32_e32 v59, 16, v191
	v_and_b32_e32 v177, 0xffff0000, v191
	v_fmac_f32_e32 v66, v59, v200
	v_fmac_f32_e32 v67, v177, v201
	v_lshlrev_b32_e32 v165, 16, v195
	v_and_b32_e32 v166, 0xffff0000, v195
	v_fmac_f32_e32 v70, v165, v200
	v_fmac_f32_e32 v71, v166, v201
	v_lshlrev_b32_e32 v165, 16, v188
	v_and_b32_e32 v166, 0xffff0000, v188
	v_fmac_f32_e32 v60, v165, v202
	v_fmac_f32_e32 v61, v166, v203
	v_lshlrev_b32_e32 v59, 16, v192
	v_and_b32_e32 v177, 0xffff0000, v192
	v_fmac_f32_e32 v64, v59, v202
	v_fmac_f32_e32 v65, v177, v203
	v_lshlrev_b32_e32 v165, 16, v196
	v_and_b32_e32 v166, 0xffff0000, v196
	v_fmac_f32_e32 v68, v165, v202
	v_fmac_f32_e32 v69, v166, v203
	v_lshlrev_b32_e32 v165, 16, v189
	v_and_b32_e32 v166, 0xffff0000, v189
	v_fmac_f32_e32 v62, v165, v204
	v_fmac_f32_e32 v63, v166, v205
	v_lshlrev_b32_e32 v59, 16, v193
	v_and_b32_e32 v177, 0xffff0000, v193
	v_fmac_f32_e32 v66, v59, v204
	v_fmac_f32_e32 v67, v177, v205
	v_lshlrev_b32_e32 v165, 16, v197
	v_and_b32_e32 v166, 0xffff0000, v197
	v_fmac_f32_e32 v70, v165, v204
	v_fmac_f32_e32 v71, v166, v205
	s_waitcnt vmcnt(0)
	v_lshlrev_b32_e32 v165, 16, v206
	v_and_b32_e32 v166, 0xffff0000, v206
	v_fmac_f32_e32 v60, v165, v218
	v_fmac_f32_e32 v61, v166, v219
	v_lshlrev_b32_e32 v59, 16, v210
	v_and_b32_e32 v177, 0xffff0000, v210
	v_fmac_f32_e32 v64, v59, v218
	v_fmac_f32_e32 v65, v177, v219
	v_lshlrev_b32_e32 v165, 16, v214
	v_and_b32_e32 v166, 0xffff0000, v214
	v_fmac_f32_e32 v68, v165, v218
	v_fmac_f32_e32 v69, v166, v219
	v_lshlrev_b32_e32 v165, 16, v207
	v_and_b32_e32 v166, 0xffff0000, v207
	v_fmac_f32_e32 v62, v165, v220
	v_fmac_f32_e32 v63, v166, v221
	v_lshlrev_b32_e32 v59, 16, v211
	v_and_b32_e32 v177, 0xffff0000, v211
	v_fmac_f32_e32 v66, v59, v220
	v_fmac_f32_e32 v67, v177, v221
	v_lshlrev_b32_e32 v165, 16, v215
	v_and_b32_e32 v166, 0xffff0000, v215
	v_fmac_f32_e32 v70, v165, v220
	v_fmac_f32_e32 v71, v166, v221
	v_lshlrev_b32_e32 v165, 16, v208
	v_and_b32_e32 v166, 0xffff0000, v208
	v_fmac_f32_e32 v60, v165, v222
	v_fmac_f32_e32 v61, v166, v223
	v_lshlrev_b32_e32 v59, 16, v212
	v_and_b32_e32 v177, 0xffff0000, v212
	v_fmac_f32_e32 v64, v59, v222
	v_fmac_f32_e32 v65, v177, v223
	v_lshlrev_b32_e32 v165, 16, v216
	v_and_b32_e32 v166, 0xffff0000, v216
	v_fmac_f32_e32 v68, v165, v222
	v_fmac_f32_e32 v69, v166, v223
	v_lshlrev_b32_e32 v165, 16, v209
	v_and_b32_e32 v166, 0xffff0000, v209
	v_fmac_f32_e32 v62, v165, v224
	v_fmac_f32_e32 v63, v166, v225
	v_lshlrev_b32_e32 v59, 16, v213
	v_and_b32_e32 v177, 0xffff0000, v213
	v_fmac_f32_e32 v66, v59, v224
	v_fmac_f32_e32 v67, v177, v225
	v_lshlrev_b32_e32 v165, 16, v217
	v_and_b32_e32 v166, 0xffff0000, v217
	v_fmac_f32_e32 v70, v165, v224
	v_fmac_f32_e32 v71, v166, v225
	v_add_f32_e32 v60, v60, v61
	v_add_f32_e32 v62, v62, v63
	v_add_f32_e32 v6, v60, v62
	v_add_f32_e32 v64, v64, v65
	v_add_f32_e32 v66, v66, v67
	v_add_f32_e32 v168, v64, v66
	v_add_f32_e32 v68, v68, v69
	v_add_f32_e32 v70, v70, v71
	v_add_f32_e32 v169, v68, v70
	v_mov_b32_e32 v18, 0
	v_mov_b32_e32 v19, 0
	v_mov_b32_e32 v9, 0
	s_mov_b32 s78, 2
	s_branch .Lc3_epi
